# phase 0: odd waves run the bandwidth-bound xn part first and the latency-bound weight transposes / LoRA block / p->bf16 afterwards, even waves keep the old order, so streaming and small-load waits ove
# baseline (speedup 1.0000x reference)
; __global__ void __launch_bounds__(512, 2) hymba_fwd(Params p) {
;     extern __shared__ __attribute__((aligned(16))) unsigned char lds_raw[];
;     LAS unsigned char* lds = (LAS unsigned char*)lds_raw;
;     cg::grid_group grid = cg::this_grid();
;     volatile LAS unsigned* stw = (volatile LAS unsigned*)(lds + 131072);
;     if (threadIdx.x == 0) { stw[0] = 0u; stw[1] = 0u; }
;     __syncthreads();
;     const XcdBarrier xbar = xcd_barrier_post((unsigned*)(p.ws + WS_BAR), stw);
_Z9hymba_fwd6Params:
	s_mov_b64 s[100:101], s[0:1]
	s_mov_b32 s99, 0
	s_load_dwordx16 s[44:59], s[0:1], 0xc0
	s_load_dword s3, s[0:1], 0x108
	s_load_dwordx2 s[96:97], s[0:1], 0x100
	s_add_u32 s6, s0, 0x100
	s_addc_u32 s7, s1, 0
	v_and_b32_e32 v244, 0x3ff, v0
	s_waitcnt lgkmcnt(0)
	v_writelane_b32 v254, s3, 0
	v_cmp_eq_u32_e64 s[8:9], 0, v244
	s_mov_b64 s[4:5], exec
	s_nop 0
	v_writelane_b32 v254, s8, 1
	s_nop 1
	v_writelane_b32 v254, s9, 2
	s_and_b64 s[8:9], s[4:5], s[8:9]
	s_mov_b64 exec, s[8:9]
	s_cbranch_execz .LBB0_2
	s_add_i32 s3, 0, 0x20000
	v_mov_b32_e32 v1, 0
	v_mov_b32_e32 v2, s3
	s_add_i32 s3, 0, 0x20004
	ds_write_b32 v2, v1
	v_mov_b32_e32 v2, s3
	ds_write_b32 v2, v1

; __device__ __forceinline__ void phase0(const Params& p, LAS unsigned char* lds, int wid, int lane) {
;     unsigned char* ws = p.ws;
;     LAS float* scr = (LAS float*)(lds + wid * 8448);
;     const int gw = blockIdx.x * 8 + wid, NGW = gridDim.x * 8;
;     constexpr int I1 = 16 * 112, I3 = 16 * 32, I4 = 16 * 176, I5 = 44 * 32, I6 = 4 * 32, I7 = 16 * 32, NIT = I1 + I3 + I4 + I5 + I6 + I7;
;     for (int it = gw; it < NIT; it += NGW) {
;         int r = it;
;         if (r < I1) { const int kb = r / 112, nb = r % 112; transpose_item(p.in[7], 3424, nb * 32 < 3424 ? nb * 32 : -1, (bf16_t*)(ws + WS_W1T), 1024, nb * 32, kb * 64, scr, lane); continue; } r -= I1;
.Lp0_again:
	s_load_dwordx16 s[8:23], s[0:1], 0x0
	v_mov_b32_e32 v16, v244
	s_lshl_b32 s88, s2, 3
	v_readfirstlane_b32 s3, v16
	s_waitcnt lgkmcnt(0)
	v_writelane_b32 v254, s8, 5
	s_ashr_i32 s4, s3, 6
	s_lshl_b32 s92, s96, 3
	v_writelane_b32 v254, s9, 6
	v_writelane_b32 v254, s10, 7
	v_writelane_b32 v254, s11, 8
	v_writelane_b32 v254, s12, 9
	v_writelane_b32 v254, s13, 10
	v_writelane_b32 v254, s14, 11
	v_writelane_b32 v254, s15, 12
	v_writelane_b32 v254, s16, 13
	v_writelane_b32 v254, s17, 14
	v_writelane_b32 v254, s18, 15
	v_writelane_b32 v254, s19, 16
	v_writelane_b32 v254, s20, 17
	v_writelane_b32 v254, s21, 18
	v_writelane_b32 v254, s22, 19
	v_writelane_b32 v254, s23, 20
	s_load_dwordx16 s[8:23], s[0:1], 0x80
	v_and_b32_e32 v1, 63, v16
	s_waitcnt lgkmcnt(0)
	v_writelane_b32 v254, s8, 21
	s_nop 1
	v_writelane_b32 v254, s9, 22
	v_writelane_b32 v254, s10, 23
	v_writelane_b32 v254, s11, 24
	v_writelane_b32 v254, s12, 25
	v_writelane_b32 v254, s13, 26
	v_writelane_b32 v254, s14, 27
	v_writelane_b32 v254, s15, 28
	v_writelane_b32 v254, s16, 29
	v_writelane_b32 v254, s17, 30
	v_writelane_b32 v254, s18, 31
	v_writelane_b32 v254, s19, 32
	v_writelane_b32 v254, s20, 33
	v_writelane_b32 v254, s21, 34
	v_writelane_b32 v254, s22, 35
	v_writelane_b32 v254, s23, 36
	s_add_i32 s8, s4, s88
	s_cmp_lg_u32 s99, 0
	s_cbranch_scc1 .Lp0_rest
	s_bitcmp1_b32 s4, 0
	s_cbranch_scc0 .Lp0_rest
	s_mov_b32 s99, 1
	s_branch .Lp0_xn
.Lp0_rest:
	s_cmpk_gt_i32 s8, 0x1bff
	s_cbranch_scc1 .LBB0_56
	v_lshlrev_b32_e32 v2, 3, v1
	v_and_b32_e32 v2, 56, v2
	s_load_dwordx16 s[60:75], s[0:1], 0x0
	s_mul_i32 s3, s4, 0x2100
	v_lshrrev_b32_e32 v47, 3, v1
	v_mul_u32_u24_e32 v8, 0x84, v2
	v_lshlrev_b32_e32 v2, 1, v2
	v_mov_b32_e32 v3, 0
	s_add_i32 s5, s3, 0
	v_lshl_add_u64 v[4:5], s[58:59], 0, v[2:3]
	v_lshlrev_b32_e32 v2, 2, v47
	v_add3_u32 v48, s5, v8, v2
	v_lshlrev_b32_e32 v2, 2, v16
	v_and_b32_e32 v14, 0x7c, v2
	v_mov_b32_e32 v15, v3
	v_lshrrev_b32_e32 v46, 5, v1
	s_mov_b64 s[12:13], 0x1c00000
	s_waitcnt lgkmcnt(0)
	v_lshl_add_u64 v[20:21], s[74:75], 0, v[14:15]
	s_load_dwordx16 s[60:75], s[0:1], 0x80
	v_lshl_add_u64 v[6:7], v[4:5], 0, s[12:13]
	s_mov_b64 s[12:13], 0x1b80000
	v_mul_u32_u24_e32 v2, 0x84, v46
	v_lshl_add_u64 v[8:9], v[4:5], 0, s[12:13]
	s_mov_b64 s[12:13], 0x1600000
	v_or_b32_e32 v2, s3, v2
	v_lshl_add_u64 v[10:11], v[4:5], 0, s[12:13]
	s_mov_b64 s[12:13], 0xb00000
	v_add3_u32 v52, v2, v14, 0
	s_lshl_b32 s3, s2, 4
	s_lshl_b32 s5, s4, 1
	v_bfe_u32 v2, v16, 5, 1
	v_lshl_add_u64 v[12:13], v[4:5], 0, s[12:13]
	s_mov_b64 s[12:13], 0x900000
	s_add_i32 s3, s3, s5
	s_lshl_b32 s5, s2, 8
	s_lshl_b32 s4, s4, 5
	v_mul_hi_u32_u24_e32 v17, 0x2c00, v2
	v_mul_u32_u24_e32 v2, 0x2c00, v2
	s_mov_b32 s11, 0
	v_or_b32_e32 v49, 8, v47
	v_or_b32_e32 v50, 16, v47
	v_or_b32_e32 v51, 24, v47
	v_or_b32_e32 v53, 0xffffcc0e, v46
	s_lshl_b32 s9, s96, 4
	s_add_i32 s16, s5, s4
	s_lshl_b32 s17, s96, 8
	v_or_b32_e32 v54, 0xffffcc0c, v46
	v_or_b32_e32 v55, 0xffffcc0a, v46
	v_or_b32_e32 v56, 0xffffcc08, v46
	v_or_b32_e32 v57, 0xffffcc06, v46
	v_or_b32_e32 v58, 0xffffcc04, v46
	v_or_b32_e32 v59, 0xffffcc02, v46
	v_or_b32_e32 v60, 0xffffcc00, v46
	v_or_b32_e32 v61, 0xffffcd0e, v46
	v_or_b32_e32 v62, 0xffffcd0c, v46
	v_or_b32_e32 v63, 0xffffcd0a, v46
	v_or_b32_e32 v64, 0xffffcd08, v46
	v_or_b32_e32 v65, 0xffffcd06, v46
	v_or_b32_e32 v66, 0xffffcd04, v46
	v_or_b32_e32 v67, 0xffffcd02, v46
	v_or_b32_e32 v68, 0xffffcd00, v46
	v_or_b32_e32 v69, 0xffffd80e, v46
	v_or_b32_e32 v70, 0xffffd80c, v46
	v_or_b32_e32 v71, 0xffffd80a, v46
	v_or_b32_e32 v72, 0xffffd808, v46
	v_or_b32_e32 v73, 0xffffd806, v46
	v_or_b32_e32 v74, 0xffffd804, v46
	v_or_b32_e32 v75, 0xffffd802, v46
	v_or_b32_e32 v76, 0xffffd800, v46
	v_or_b32_e32 v77, 14, v46
	v_or_b32_e32 v78, 12, v46
	v_or_b32_e32 v79, 10, v46
	v_or_b32_e32 v80, 8, v46
	v_or_b32_e32 v16, v2, v14
	v_or_b32_e32 v81, 0xfffff20e, v46
	v_or_b32_e32 v82, 0xfffff20c, v46
	v_or_b32_e32 v83, 0xfffff20a, v46
	v_or_b32_e32 v84, 0xfffff208, v46
	v_or_b32_e32 v85, 0xfffff206, v46
	v_or_b32_e32 v86, 0xfffff204, v46
	v_or_b32_e32 v87, 0xfffff202, v46
	v_or_b32_e32 v88, 0xfffff200, v46
	s_movk_i32 s18, 0x3580
	s_mov_b32 s19, s8
	v_lshl_add_u64 v[18:19], v[4:5], 0, s[12:13]
	v_lshl_add_u64 v[22:23], s[52:53], 0, v[14:15]
	v_lshl_add_u64 v[24:25], s[50:51], 0, v[14:15]
	v_lshl_add_u64 v[26:27], s[48:49], 0, v[14:15]
	s_waitcnt lgkmcnt(0)
	v_lshl_add_u64 v[28:29], s[74:75], 0, v[14:15]
	s_branch .LBB0_9

; __device__ __forceinline__ unsigned pk2(float lo, float hi) { unsigned r; asm("v_cvt_pk_bf16_f32 %0, %1, %2" : "=v"(r) : "v"(lo), "v"(hi)); return r; }
; __device__ __forceinline__ void phase0(const Params& p, LAS unsigned char* lds, int wid, int lane) {
;     ...
;     {
;         const float* nw = p.in[2]; f32x4 wv[4];
; #pragma unroll
;         for (int j = 0; j < 4; ++j) wv[j] = *(const f32x4*)(nw + 4 * lane + 256 * j);
;         bf16_t* XN = (bf16_t*)(ws + WS_XN);
;         for (int t = gw; t < M_TOK; t += NGW) { const float* xr = p.in[0] + (size_t)t * DM; f32x4 v[4]; float s = 0.f;
; #pragma unroll
;             for (int j = 0; j < 4; ++j) { v[j] = __builtin_nontemporal_load((const f32x4*)(xr + 4 * lane + 256 * j)); s += (v[j][0] * v[j][0] + v[j][1] * v[j][1]) + (v[j][2] * v[j][2] + v[j][3] * v[j][3]); }
;             const float rs = rsqrtf(wave_sum(s) * (1.0f / DM) + NEPS);
; #pragma unroll
;             for (int j = 0; j < 4; ++j) { const f32x4 o = v[j] * rs * wv[j]; u32x2 w; w.x = pk2(o[0], o[1]); w.y = pk2(o[2], o[3]); *(u32x2*)(XN + (size_t)t * DM + 4 * lane + 256 * j) = w; } }
.LBB0_92:
	s_or_b64 exec, exec, s[10:11]
	s_cmp_eq_u32 s99, 2
	s_cbranch_scc1 .LBB0_95
.Lp0_xn:
	s_cmp_lt_i32 s8, 0x8000
	s_cbranch_scc0 .LBB0_95
	v_readlane_b32 s60, v254, 5
	v_lshlrev_b32_e32 v20, 4, v1
	v_readlane_b32 s64, v254, 9
	v_readlane_b32 s65, v254, 10
	s_nop 4
	global_load_dwordx4 v[2:5], v20, s[64:65]
	global_load_dwordx4 v[6:9], v20, s[64:65] offset:1024
	global_load_dwordx4 v[10:13], v20, s[64:65] offset:2048
	global_load_dwordx4 v[14:17], v20, s[64:65] offset:3072
	v_mbcnt_lo_u32_b32 v18, -1, 0
	v_mbcnt_hi_u32_b32 v18, -1, v18
	v_and_b32_e32 v19, 64, v18
	v_add_u32_e32 v19, 64, v19
	v_xor_b32_e32 v21, 1, v18
	v_cmp_lt_i32_e32 vcc, v21, v19
	s_ashr_i32 s9, s8, 31
	s_lshl_b64 s[0:1], s[8:9], 11
	v_cndmask_b32_e32 v21, v18, v21, vcc
	v_lshlrev_b32_e32 v22, 2, v21
	v_xor_b32_e32 v21, 2, v18
	v_cmp_lt_i32_e32 vcc, v21, v19
	s_add_u32 s0, s58, s0
	v_lshlrev_b32_e32 v28, 3, v1
	v_cndmask_b32_e32 v21, v18, v21, vcc
	v_lshlrev_b32_e32 v23, 2, v21
	v_xor_b32_e32 v21, 4, v18
	v_cmp_lt_i32_e32 vcc, v21, v19
	v_mov_b32_e32 v29, 0
	s_addc_u32 s1, s59, s1
	v_cndmask_b32_e32 v21, v18, v21, vcc
	v_lshlrev_b32_e32 v24, 2, v21
	v_xor_b32_e32 v21, 8, v18
	v_cmp_lt_i32_e32 vcc, v21, v19
	s_ashr_i32 s93, s92, 31
	s_lshl_b64 s[4:5], s[8:9], 12
	v_cndmask_b32_e32 v21, v18, v21, vcc
	v_lshlrev_b32_e32 v25, 2, v21
	v_xor_b32_e32 v21, 16, v18
	v_cmp_lt_i32_e32 vcc, v21, v19
	v_readlane_b32 s61, v254, 6
	v_mov_b32_e32 v1, 0x358637bd
	v_cndmask_b32_e32 v21, v18, v21, vcc
	v_lshlrev_b32_e32 v26, 2, v21
	v_xor_b32_e32 v21, 32, v18
	v_cmp_lt_i32_e32 vcc, v21, v19
	s_mov_b32 s3, 0x800000
	v_readlane_b32 s62, v254, 7
	v_cndmask_b32_e32 v18, v18, v21, vcc
	v_lshlrev_b32_e32 v27, 2, v18
	v_lshl_add_u64 v[18:19], s[0:1], 0, v[28:29]
	s_mov_b64 s[0:1], 0x3000000
	v_lshl_add_u64 v[18:19], v[18:19], 0, s[0:1]
	s_lshl_b64 s[0:1], s[92:93], 11
	s_add_u32 s4, s60, s4
	v_mov_b32_e32 v21, v29
	s_addc_u32 s5, s61, s5
	v_lshl_add_u64 v[20:21], s[4:5], 0, v[20:21]
	s_mov_b64 s[4:5], 0xc00
	v_lshl_add_u64 v[20:21], v[20:21], 0, s[4:5]
	s_lshl_b64 s[4:5], s[92:93], 12
	v_readlane_b32 s63, v254, 8
	v_readlane_b32 s66, v254, 11
	v_readlane_b32 s67, v254, 12
	v_readlane_b32 s68, v254, 13
	v_readlane_b32 s69, v254, 14
	v_readlane_b32 s70, v254, 15
	v_readlane_b32 s71, v254, 16
	v_readlane_b32 s72, v254, 17
	v_readlane_b32 s73, v254, 18
	v_readlane_b32 s74, v254, 19
	v_readlane_b32 s75, v254, 20

; __device__ __forceinline__ unsigned pk2(float lo, float hi) { unsigned r; asm("v_cvt_pk_bf16_f32 %0, %1, %2" : "=v"(r) : "v"(lo), "v"(hi)); return r; }
; __device__ __forceinline__ void phase0(const Params& p, LAS unsigned char* lds, int wid, int lane) {
;     ...
;         for (int t = gw; t < M_TOK; t += NGW) { const float* xr = p.in[0] + (size_t)t * DM; f32x4 v[4]; float s = 0.f;
; #pragma unroll
;             for (int j = 0; j < 4; ++j) { v[j] = __builtin_nontemporal_load((const f32x4*)(xr + 4 * lane + 256 * j)); s += (v[j][0] * v[j][0] + v[j][1] * v[j][1]) + (v[j][2] * v[j][2] + v[j][3] * v[j][3]); }
;             const float rs = rsqrtf(wave_sum(s) * (1.0f / DM) + NEPS);
; #pragma unroll
;             for (int j = 0; j < 4; ++j) { const f32x4 o = v[j] * rs * wv[j]; u32x2 w; w.x = pk2(o[0], o[1]); w.y = pk2(o[2], o[3]); *(u32x2*)(XN + (size_t)t * DM + 4 * lane + 256 * j) = w; } }
;     }
; }
.LBB0_95:
	s_cmp_eq_u32 s99, 1
	s_cbranch_scc0 .Lp0_done
	s_mov_b32 s99, 2
	s_mov_b64 s[0:1], s[100:101]
	s_load_dwordx16 s[44:59], s[0:1], 0xc0
	s_waitcnt lgkmcnt(0)
	s_branch .Lp0_again
